# GEMM stagger split point moved: waves 4-7 take the barrier after 12 of 32 MFMAs
# speedup vs baseline: 1.0073x; 1.0073x over previous
; DI void lds_barrier() { asm volatile("s_waitcnt lgkmcnt(0)\n\ts_barrier" ::: "memory"); }
; #define ISSUE() do { const int ka_ = (kp + koff >= nk) ? kp + koff - nk : kp + koff; \
;                 glds16x5(A + ka_ * 32, pbt + (size_t)(ka_ >> 1) * 16384 + (ka_ & 1) * 32, va, vb0, vb1, vb2, vb3, lbase + (unsigned)sp * H5_STAGE); \
;                 ++kp; if (kp == nk) { kp = 0; ++tp; pbt += (size_t)512 * K; if (tp == ntw) { tp = 0; pbt = Bt; } } sp = (sp == 2) ? 0 : sp + 1; } while (0)
; DI void run_jobs(const Params& P, int rb, int jj_lo, int jj_hi, unsigned char* smem) {
;     ...
; #pragma unroll
;                 for (int mt = 0; mt < 4; ++mt)
; #pragma unroll
;                     for (int n_ = 0; n_ < 8; ++n_) acc[mt][n_] = __builtin_amdgcn_mfma_f32_16x16x32_bf16(bfr[n_], af[mt], acc[mt][n_], 0, 0, 0);
;                 if (s + 2 < S) asm volatile("s_waitcnt vmcnt(5)" ::: "memory");
;                 else asm volatile("s_waitcnt vmcnt(0)" ::: "memory");
;                 lds_barrier();
;                 if (s + 3 < S) ISSUE();
.Lg_y:
	s_nop 0
	s_add_i32 s21, s61, 3
	s_cmp_ge_u32 s21, s54
	s_cbranch_scc1 .Lg_y_plain
	s_add_i32 s8, s53, s57
	s_cmp_ge_i32 s8, s52
	s_cselect_b32 s9, s52, 0
	s_sub_i32 s21, s8, s9
	s_lshl_b32 s8, s21, 5
	s_ashr_i32 s9, s8, 31
	s_lshl_b64 s[8:9], s[8:9], 1
	s_add_u32 s8, s28, s8
	s_addc_u32 s9, s29, s9
	s_ashr_i32 s64, s21, 1
	s_ashr_i32 s65, s64, 31
	s_lshl_b64 s[64:65], s[64:65], 15
	s_add_u32 s63, s4, s64
	s_addc_u32 s65, s58, s65
	s_lshl_b32 s21, s21, 14
	s_and_b32 s21, s21, 0x4000
	s_add_u32 s64, s63, s21
	s_mul_i32 s21, s23, 0xa000
	s_addc_u32 s65, s65, 0
	s_add_i32 s21, s21, s55
	s_mov_b32 m0, s21
	s_waitcnt lgkmcnt(10)
	v_mfma_f32_16x16x32_bf16 v[124:127], v[140:143], v[172:175], v[124:127]
	s_waitcnt lgkmcnt(9)
	v_mfma_f32_16x16x32_bf16 v[120:123], v[144:147], v[172:175], v[120:123]
	s_waitcnt lgkmcnt(8)
	v_mfma_f32_16x16x32_bf16 v[116:119], v[148:151], v[172:175], v[116:119]
	s_waitcnt lgkmcnt(7)
	v_mfma_f32_16x16x32_bf16 v[112:115], v[152:155], v[172:175], v[112:115]
	s_waitcnt lgkmcnt(6)
	v_mfma_f32_16x16x32_bf16 v[108:111], v[156:159], v[172:175], v[108:111]
	s_waitcnt lgkmcnt(5)
	v_mfma_f32_16x16x32_bf16 v[104:107], v[160:163], v[172:175], v[104:107]
	s_waitcnt lgkmcnt(4)
	v_mfma_f32_16x16x32_bf16 v[100:103], v[164:167], v[172:175], v[100:103]
	s_waitcnt lgkmcnt(3)
	v_mfma_f32_16x16x32_bf16 v[96:99], v[132:135], v[172:175], v[96:99]
	s_waitcnt lgkmcnt(2)
	v_mfma_f32_16x16x32_bf16 v[92:95], v[140:143], v[168:171], v[92:95]
	v_mfma_f32_16x16x32_bf16 v[88:91], v[144:147], v[168:171], v[88:91]
	v_mfma_f32_16x16x32_bf16 v[84:87], v[148:151], v[168:171], v[84:87]
	v_mfma_f32_16x16x32_bf16 v[80:83], v[152:155], v[168:171], v[80:83]
	s_waitcnt vmcnt(5)
	s_waitcnt lgkmcnt(0)
	s_barrier
	v_mfma_f32_16x16x32_bf16 v[76:79], v[156:159], v[168:171], v[76:79]
	global_load_lds_dwordx4 v239, s[8:9]
	s_add_u32 m0, m0, 0x2000
	v_mfma_f32_16x16x32_bf16 v[72:75], v[160:163], v[168:171], v[72:75]
	v_mfma_f32_16x16x32_bf16 v[68:71], v[164:167], v[168:171], v[68:71]
	global_load_lds_dwordx4 v237, s[64:65]
	s_add_u32 m0, m0, 0x2000
	v_mfma_f32_16x16x32_bf16 v[64:67], v[132:135], v[168:171], v[64:67]
	s_waitcnt lgkmcnt(1)
	v_mfma_f32_16x16x32_bf16 v[60:63], v[140:143], v[136:139], v[60:63]
	global_load_lds_dwordx4 v240, s[64:65]
	s_add_u32 m0, m0, 0x2000
	v_mfma_f32_16x16x32_bf16 v[56:59], v[144:147], v[136:139], v[56:59]
	v_mfma_f32_16x16x32_bf16 v[52:55], v[148:151], v[136:139], v[52:55]
	global_load_lds_dwordx4 v238, s[64:65]
	s_add_u32 m0, m0, 0x2000
	v_mfma_f32_16x16x32_bf16 v[48:51], v[152:155], v[136:139], v[48:51]
	v_mfma_f32_16x16x32_bf16 v[44:47], v[156:159], v[136:139], v[44:47]
	global_load_lds_dwordx4 v241, s[64:65]
	v_mfma_f32_16x16x32_bf16 v[40:43], v[160:163], v[136:139], v[40:43]
	v_mfma_f32_16x16x32_bf16 v[36:39], v[164:167], v[136:139], v[36:39]
	v_mfma_f32_16x16x32_bf16 v[32:35], v[132:135], v[136:139], v[32:35]
	s_waitcnt lgkmcnt(0)
	v_mfma_f32_16x16x32_bf16 v[28:31], v[140:143], v[128:131], v[28:31]
	v_mfma_f32_16x16x32_bf16 v[24:27], v[144:147], v[128:131], v[24:27]
	v_mfma_f32_16x16x32_bf16 v[20:23], v[148:151], v[128:131], v[20:23]
	v_mfma_f32_16x16x32_bf16 v[16:19], v[152:155], v[128:131], v[16:19]
	v_mfma_f32_16x16x32_bf16 v[12:15], v[156:159], v[128:131], v[12:15]
	v_mfma_f32_16x16x32_bf16 v[8:11], v[160:163], v[128:131], v[8:11]
	v_mfma_f32_16x16x32_bf16 v[4:7], v[164:167], v[128:131], v[4:7]
	v_mfma_f32_16x16x32_bf16 v[0:3], v[132:135], v[128:131], v[0:3]
	s_add_i32 s21, s53, 1
	s_cmp_eq_u32 s21, s52
	s_cselect_b64 s[8:9], -1, 0
	s_add_i32 s53, s56, 1
	s_add_u32 s63, s4, s59
	s_addc_u32 s66, s58, 0
	s_cmp_eq_u32 s53, s22
	s_cselect_b64 s[64:65], -1, 0
	s_and_b64 s[64:65], s[64:65], exec
	s_cselect_b32 s63, s94, s63
	s_cselect_b32 s64, s95, s66
	s_cselect_b32 s53, 0, s53
	s_and_b64 s[8:9], s[8:9], exec
	s_cselect_b32 s58, s64, s58
	s_cselect_b32 s4, s63, s4
	s_cselect_b32 s56, s53, s56
	s_cselect_b32 s53, 0, s21
	s_add_i32 s8, s23, 1
	s_cmp_lg_u32 s23, 2
	s_cselect_b32 s23, s8, 0
	s_branch .LBB0_150
.Lg_y_plain:
	s_waitcnt lgkmcnt(10)
	v_mfma_f32_16x16x32_bf16 v[124:127], v[140:143], v[172:175], v[124:127]
	s_waitcnt lgkmcnt(9)
	v_mfma_f32_16x16x32_bf16 v[120:123], v[144:147], v[172:175], v[120:123]
	s_waitcnt lgkmcnt(8)
	v_mfma_f32_16x16x32_bf16 v[116:119], v[148:151], v[172:175], v[116:119]
	s_waitcnt lgkmcnt(7)
	v_mfma_f32_16x16x32_bf16 v[112:115], v[152:155], v[172:175], v[112:115]
	s_waitcnt lgkmcnt(6)
	v_mfma_f32_16x16x32_bf16 v[108:111], v[156:159], v[172:175], v[108:111]
	s_waitcnt lgkmcnt(5)
	v_mfma_f32_16x16x32_bf16 v[104:107], v[160:163], v[172:175], v[104:107]
	s_waitcnt lgkmcnt(4)
	v_mfma_f32_16x16x32_bf16 v[100:103], v[164:167], v[172:175], v[100:103]
	s_waitcnt lgkmcnt(3)
	v_mfma_f32_16x16x32_bf16 v[96:99], v[132:135], v[172:175], v[96:99]
	s_waitcnt lgkmcnt(2)
	v_mfma_f32_16x16x32_bf16 v[92:95], v[140:143], v[168:171], v[92:95]
	v_mfma_f32_16x16x32_bf16 v[88:91], v[144:147], v[168:171], v[88:91]
	v_mfma_f32_16x16x32_bf16 v[84:87], v[148:151], v[168:171], v[84:87]
	v_mfma_f32_16x16x32_bf16 v[80:83], v[152:155], v[168:171], v[80:83]
	s_add_i32 s21, s61, 2
	s_cmp_ge_u32 s21, s54
	s_cbranch_scc1 .Lg_drain_y
	s_waitcnt vmcnt(5)
	s_branch .Lg_bar_y

; DI void lds_barrier() { asm volatile("s_waitcnt lgkmcnt(0)\n\ts_barrier" ::: "memory"); }
; DI void run_jobs(const Params& P, int rb, int jj_lo, int jj_hi, unsigned char* smem) {
;     ...
; #pragma unroll
;                 for (int mt = 0; mt < 4; ++mt)
; #pragma unroll
;                     for (int n_ = 0; n_ < 8; ++n_) acc[mt][n_] = __builtin_amdgcn_mfma_f32_16x16x32_bf16(bfr[n_], af[mt], acc[mt][n_], 0, 0, 0);
;                 if (s + 2 < S) asm volatile("s_waitcnt vmcnt(5)" ::: "memory");
;                 else asm volatile("s_waitcnt vmcnt(0)" ::: "memory");
;                 lds_barrier();
.Lg_bar_y:
	s_waitcnt lgkmcnt(0)
	s_barrier
	v_mfma_f32_16x16x32_bf16 v[76:79], v[156:159], v[168:171], v[76:79]
	v_mfma_f32_16x16x32_bf16 v[72:75], v[160:163], v[168:171], v[72:75]
	v_mfma_f32_16x16x32_bf16 v[68:71], v[164:167], v[168:171], v[68:71]
	v_mfma_f32_16x16x32_bf16 v[64:67], v[132:135], v[168:171], v[64:67]
	s_waitcnt lgkmcnt(1)
	v_mfma_f32_16x16x32_bf16 v[60:63], v[140:143], v[136:139], v[60:63]
	v_mfma_f32_16x16x32_bf16 v[56:59], v[144:147], v[136:139], v[56:59]
	v_mfma_f32_16x16x32_bf16 v[52:55], v[148:151], v[136:139], v[52:55]
	v_mfma_f32_16x16x32_bf16 v[48:51], v[152:155], v[136:139], v[48:51]
	v_mfma_f32_16x16x32_bf16 v[44:47], v[156:159], v[136:139], v[44:47]
	v_mfma_f32_16x16x32_bf16 v[40:43], v[160:163], v[136:139], v[40:43]
	v_mfma_f32_16x16x32_bf16 v[36:39], v[164:167], v[136:139], v[36:39]
	v_mfma_f32_16x16x32_bf16 v[32:35], v[132:135], v[136:139], v[32:35]
	s_waitcnt lgkmcnt(0)
	v_mfma_f32_16x16x32_bf16 v[28:31], v[140:143], v[128:131], v[28:31]
	v_mfma_f32_16x16x32_bf16 v[24:27], v[144:147], v[128:131], v[24:27]
	v_mfma_f32_16x16x32_bf16 v[20:23], v[148:151], v[128:131], v[20:23]
	v_mfma_f32_16x16x32_bf16 v[16:19], v[152:155], v[128:131], v[16:19]
	v_mfma_f32_16x16x32_bf16 v[12:15], v[156:159], v[128:131], v[12:15]
	v_mfma_f32_16x16x32_bf16 v[8:11], v[160:163], v[128:131], v[8:11]
	v_mfma_f32_16x16x32_bf16 v[4:7], v[164:167], v[128:131], v[4:7]
	v_mfma_f32_16x16x32_bf16 v[0:3], v[132:135], v[128:131], v[0:3]
